# r1: cold K/V row loads issued at the item top before the gate-row burst (older in vmcnt order) so they overlap build_cum; gate-row prefetch depth 15 -> 13
# speedup vs baseline: 1.0010x; 1.0010x over previous
; __device__ __forceinline__ void build_cum(const Args& a, int L, int hl, long R0, const bf16_t* __restrict__ proj, LAS unsigned char* lds) {
;     ...
;     const int k = tid & 63, dir = (tid >> 6) & 1, isub = tid >> 7;
;     if (hl < 4) {
;         float gw[16];
; #pragma unroll
;         for (int r = 0; r < 16; ++r) gw[r] = a.gate_w[((size_t)(L * 2 + dir) * 16 + r) * 256 + hl * 64 + k];
;         const float gb = a.gate_b[(L * 2 + dir) * 256 + hl * 64 + k];
; #pragma unroll 4
;         for (int it = 0; it < 16; ++it) { const int i = isub + 4 * it; const bf16_t* ga = proj + (R0 + i) * LD + GAF + dir * 16;
;             const u32x4 g0 = *(const u32x4*)ga, g1 = *(const u32x4*)(ga + 8);
;             float x = gb;
;             x += gw[0] * bflo(g0.x) + gw[1] * bfhi(g0.x) + gw[2] * bflo(g0.y) + gw[3] * bfhi(g0.y) + gw[4] * bflo(g0.z) + gw[5] * bfhi(g0.z) + gw[6] * bflo(g0.w) + gw[7] * bfhi(g0.w);
;             x += gw[8] * bflo(g1.x) + gw[9] * bfhi(g1.x) + gw[10] * bflo(g1.y) + gw[11] * bfhi(g1.y) + gw[12] * bflo(g1.z) + gw[13] * bfhi(g1.z) + gw[14] * bflo(g1.w) + gw[15] * bfhi(g1.w);
;             cum[(dir * 64 + i) * 64 + k] = logsigmoidf(x) * (1.0f / 16.0f); }
;     } else {
;         const float lg = logsigmoidf(a.decay_logit[(L * 2 + dir) * 4 + (hl - 4)]);
; #pragma unroll 4
;         for (int it = 0; it < 16; ++it) cum[(dir * 64 + isub + 4 * it) * 64 + k] = lg;
;     }
; __device__ __forceinline__ void r1_item(const Args& a, int L, int item, LAS unsigned char* lds) {
;     ...
;     if (tid < 256) { const int i = (tid >> 2) & 63, g = tid & 3; const int kcol = hl < 4 ? GK + hl * 64 : RK + (hl - 4) * 64;
;         float va[8], vb[8]; load_qk16(a, proj + (R0 + i) * LD + kcol, hl, c * 64 + i, g, va, vb);
; #pragma unroll
;         for (int dir = 0; dir < 2; ++dir) { const int lastrow = dir == 0 ? 63 : 64;
; #pragma unroll
;             for (int e = 0; e < 8; ++e) { const int ka = g * 8 + e, kb = 32 + g * 8 + e;
;                 const float wa = __expf(cum[lastrow * 64 + ka] - cum[(dir * 64 + i) * 64 + ka]), wb = __expf(cum[lastrow * 64 + kb] - cum[(dir * 64 + i) * 64 + kb]);
;                 KeT[(dir * 64 + ka) * PT + i] = (bf16_t)f2bf(va[e] * wa); KeT[(dir * 64 + kb) * PT + i] = (bf16_t)f2bf(vb[e] * wb); } }
;     } else { const int t2 = tid - 256, j = t2 >> 2, vg = t2 & 3; const int vcol = hl < 4 ? GV + hl * 128 : RV + (hl - 4) * 128;
.LBB0_158:
	v_mov_b32_e32 v34, v206
	s_bfe_u32 s14, s13, 0x30006
	v_mov_b32_e32 v20, v206
	s_waitcnt lgkmcnt(0)
	s_barrier
	v_bfe_u32 v172, v34, 2, 6
	v_and_b32_e32 v173, 3, v34
	v_readfirstlane_b32 s101, v34
	s_lshr_b32 s100, s13, 9
	s_mul_i32 s100, s100, 0x3200000
	s_and_b32 s0, s13, 63
	s_mul_i32 s0, s0, 0xc8000
	s_add_i32 s100, s100, s0
	v_mul_u32_u24_e32 v172, 0x3200, v172
	s_add_i32 s100, s100, 0x1af00000
	s_cmp_lt_u32 s14, 4
	s_movk_i32 s0, 0x1200
	s_lshr_b32 s101, s101, 8
	s_cmp_eq_u32 s101, 0
	s_cbranch_scc0 .Lr1_vpath
	s_cmp_lt_u32 s14, 4
	s_cselect_b32 s0, 0xd00, s0
	s_lshl_b32 s1, s14, 6
	s_add_i32 s0, s0, s1
	s_lshl_b32 s0, s0, 1
	s_add_i32 s100, s100, s0
	s_add_u32 s100, s98, s100
	s_addc_u32 s101, s99, 0
	v_lshl_add_u32 v172, v173, 4, v172
	global_load_dwordx4 v[156:159], v172, s[100:101]
	global_load_dwordx4 v[160:163], v172, s[100:101] offset:64
	s_branch .Lr1_kvdone
.Lr1_vpath:
	s_cmp_lt_u32 s14, 4
	s_cselect_b32 s0, 0xe00, s0
	s_lshl_b32 s1, s14, 7
	s_add_i32 s0, s0, s1
	s_lshl_b32 s0, s0, 1
	s_add_i32 s100, s100, s0
	s_add_u32 s100, s98, s100
	s_addc_u32 s101, s99, 0
	v_lshl_add_u32 v172, v173, 6, v172
	global_load_dwordx4 v[156:159], v172, s[100:101]
	global_load_dwordx4 v[160:163], v172, s[100:101] offset:16
	global_load_dwordx4 v[164:167], v172, s[100:101] offset:32
	global_load_dwordx4 v[168:171], v172, s[100:101] offset:48
.Lr1_kvdone:
	s_cmp_lt_u32 s14, 4
	v_and_b32_e32 v21, 63, v20
	v_ashrrev_i32_e32 v18, 7, v20
	v_bfe_u32 v19, v20, 6, 1
	s_cselect_b64 s[8:9], -1, 0
	s_cmp_gt_u32 s14, 3
	s_mov_b64 s[0:1], -1
	v_lshlrev_b32_e32 v23, 8, v18
	v_lshlrev_b32_e32 v0, 2, v21
	s_cbranch_scc0 .LBB0_162
	v_readlane_b32 s0, v254, 42
	s_add_i32 s0, s0, s14
	s_mov_b32 s1, 1
	v_lshl_add_u32 v2, v19, 2, s0
	v_ashrrev_i32_e32 v3, 31, v2
	v_lshl_add_u64 v[2:3], v[2:3], 2, s[50:51]
	global_load_dword v3, v[2:3], off
	s_mov_b32 s0, 0
	s_mov_b32 s4, 16
	s_waitcnt vmcnt(0) lgkmcnt(0)
	v_mul_f32_e64 v2, |v3|, s95
	v_exp_f32_e32 v4, v2
	v_max_f32_e32 v3, v3, v3
	v_lshl_add_u32 v2, v19, 14, 0
	v_min_f32_e32 v3, 0, v3
	v_add_f32_e32 v4, 1.0, v4
	v_cmp_gt_f32_e32 vcc, s34, v4
	v_add3_u32 v2, v2, v23, v0
	s_nop 0
	v_cndmask_b32_e64 v5, 0, 32, vcc
	v_ldexp_f32 v4, v4, v5
	v_log_f32_e32 v4, v4
	v_cndmask_b32_e32 v5, 0, v210, vcc
	v_mul_f32_e32 v6, 0x3f317217, v4
	v_fma_f32 v6, v4, s35, -v6
	v_fmac_f32_e32 v6, 0x3377d1cf, v4
	v_fmac_f32_e32 v6, 0x3f317217, v4
	v_cmp_lt_f32_e64 vcc, |v4|, s73
	s_nop 1
	v_cndmask_b32_e32 v4, v4, v6, vcc
	v_sub_f32_e32 v4, v4, v5
	v_sub_f32_e32 v3, v3, v4

; __device__ __forceinline__ float logsigmoidf(float x) { return fminf(x, 0.f) - __logf(1.f + __expf(-fabsf(x))); }
; __device__ __forceinline__ void build_cum(const Args& a, int L, int hl, long R0, const bf16_t* __restrict__ proj, LAS unsigned char* lds) {
;     ...
;         for (int it = 0; it < 16; ++it) { const int i = isub + 4 * it; const bf16_t* ga = proj + (R0 + i) * LD + GAF + dir * 16;
;             const u32x4 g0 = *(const u32x4*)ga, g1 = *(const u32x4*)(ga + 8);
;             float x = gb;
;             x += gw[0] * bflo(g0.x) + gw[1] * bfhi(g0.x) + gw[2] * bflo(g0.y) + gw[3] * bfhi(g0.y) + gw[4] * bflo(g0.z) + gw[5] * bfhi(g0.z) + gw[6] * bflo(g0.w) + gw[7] * bfhi(g0.w);
;             x += gw[8] * bflo(g1.x) + gw[9] * bfhi(g1.x) + gw[10] * bflo(g1.y) + gw[11] * bfhi(g1.y) + gw[12] * bflo(g1.z) + gw[13] * bfhi(g1.z) + gw[14] * bflo(g1.w) + gw[15] * bfhi(g1.w);
;             cum[(dir * 64 + i) * 64 + k] = logsigmoidf(x) * (1.0f / 16.0f); }
.LBB0_164:
	s_mov_b32 s10, 0x1af03000
	s_mov_b32 s11, 0
	v_lshl_add_u64 v[32:33], v[18:19], 0, s[10:11]
	s_mov_b32 s10, 0xc800
	global_load_dwordx4 v[52:55], v[32:33], off
	global_load_dwordx4 v[56:59], v[32:33], off offset:16
	v_lshl_add_u64 v[32:33], v[32:33], 0, s[10:11]
	global_load_dwordx4 v[60:63], v[32:33], off
	global_load_dwordx4 v[64:67], v[32:33], off offset:16
	v_lshl_add_u64 v[32:33], v[32:33], 0, s[10:11]
	global_load_dwordx4 v[68:71], v[32:33], off
	global_load_dwordx4 v[72:75], v[32:33], off offset:16
	v_lshl_add_u64 v[32:33], v[32:33], 0, s[10:11]
	global_load_dwordx4 v[76:79], v[32:33], off
	global_load_dwordx4 v[80:83], v[32:33], off offset:16
	v_lshl_add_u64 v[32:33], v[32:33], 0, s[10:11]
	global_load_dwordx4 v[84:87], v[32:33], off
	global_load_dwordx4 v[88:91], v[32:33], off offset:16
	v_lshl_add_u64 v[32:33], v[32:33], 0, s[10:11]
	global_load_dwordx4 v[92:95], v[32:33], off
	global_load_dwordx4 v[96:99], v[32:33], off offset:16
	v_lshl_add_u64 v[32:33], v[32:33], 0, s[10:11]
	global_load_dwordx4 v[100:103], v[32:33], off
	global_load_dwordx4 v[104:107], v[32:33], off offset:16
	v_lshl_add_u64 v[32:33], v[32:33], 0, s[10:11]
	global_load_dwordx4 v[108:111], v[32:33], off
	global_load_dwordx4 v[112:115], v[32:33], off offset:16
	v_lshl_add_u64 v[32:33], v[32:33], 0, s[10:11]
	global_load_dwordx4 v[116:119], v[32:33], off
	global_load_dwordx4 v[120:123], v[32:33], off offset:16
	v_lshl_add_u64 v[32:33], v[32:33], 0, s[10:11]
	global_load_dwordx4 v[124:127], v[32:33], off
	global_load_dwordx4 v[128:131], v[32:33], off offset:16
	v_lshl_add_u64 v[32:33], v[32:33], 0, s[10:11]
	global_load_dwordx4 v[132:135], v[32:33], off
	global_load_dwordx4 v[136:139], v[32:33], off offset:16
	v_lshl_add_u64 v[32:33], v[32:33], 0, s[10:11]
	global_load_dwordx4 v[140:143], v[32:33], off
	global_load_dwordx4 v[144:147], v[32:33], off offset:16
	v_lshl_add_u64 v[32:33], v[32:33], 0, s[10:11]
	global_load_dwordx4 v[148:151], v[32:33], off
	global_load_dwordx4 v[152:155], v[32:33], off offset:16
	v_lshl_add_u64 v[32:33], v[32:33], 0, s[10:11]
	s_waitcnt vmcnt(24)
	v_and_b32_e32 v38, 0xffff0000, v52
	v_and_b32_e32 v39, 0xffff0000, v56
	v_lshlrev_b32_e32 v37, 16, v56
	v_lshlrev_b32_e32 v36, 16, v52
	v_pk_mul_f32 v[38:39], v[4:5], v[38:39]
	v_and_b32_e32 v30, 0xffff0000, v53
	v_pk_fma_f32 v[36:37], v[2:3], v[36:37], v[38:39]
	v_lshlrev_b32_e32 v39, 16, v57
	v_lshlrev_b32_e32 v38, 16, v53
	v_pk_fma_f32 v[36:37], v[6:7], v[38:39], v[36:37]
	v_and_b32_e32 v31, 0xffff0000, v57
	v_pk_fma_f32 v[26:27], v[8:9], v[30:31], v[36:37]
	v_lshlrev_b32_e32 v31, 16, v58
	v_lshlrev_b32_e32 v30, 16, v54
	v_pk_fma_f32 v[26:27], v[10:11], v[30:31], v[26:27]
	v_and_b32_e32 v31, 0xffff0000, v58
	v_and_b32_e32 v30, 0xffff0000, v54
	v_pk_fma_f32 v[26:27], v[12:13], v[30:31], v[26:27]
	v_lshlrev_b32_e32 v31, 16, v59
	v_lshlrev_b32_e32 v30, 16, v55
	v_pk_fma_f32 v[26:27], v[14:15], v[30:31], v[26:27]
	v_and_b32_e32 v31, 0xffff0000, v59
	v_and_b32_e32 v30, 0xffff0000, v55
	v_pk_fma_f32 v[26:27], v[16:17], v[30:31], v[26:27]
	s_nop 0
	v_add_f32_e32 v23, v22, v26
	v_add_f32_e32 v23, v23, v27
	v_min_f32_e32 v25, 0, v23
	v_mul_f32_e64 v23, |v23|, s95
	v_exp_f32_e32 v23, v23
	s_nop 0
	v_add_f32_e32 v23, 1.0, v23
	v_cmp_gt_f32_e32 vcc, s34, v23
	s_nop 1
	v_cndmask_b32_e64 v26, 0, 32, vcc
	v_ldexp_f32 v23, v23, v26
	v_log_f32_e32 v23, v23
	s_nop 0
	v_mul_f32_e32 v26, 0x3f317217, v23
	v_fma_f32 v26, v23, s35, -v26
	v_fmac_f32_e32 v26, 0x3377d1cf, v23
	v_fmac_f32_e32 v26, 0x3f317217, v23
	v_cmp_lt_f32_e64 s[0:1], |v23|, s73
	s_nop 1
	v_cndmask_b32_e64 v23, v23, v26, s[0:1]
	v_cndmask_b32_e32 v26, 0, v210, vcc
	v_sub_f32_e32 v23, v23, v26
	v_sub_f32_e32 v23, v25, v23
	v_mul_f32_e32 v28, 0x3d800000, v23
	global_load_dwordx4 v[52:55], v[32:33], off
	global_load_dwordx4 v[56:59], v[32:33], off offset:16
	v_lshl_add_u64 v[32:33], v[32:33], 0, s[10:11]
	s_waitcnt vmcnt(24)
	v_and_b32_e32 v38, 0xffff0000, v60
	v_and_b32_e32 v39, 0xffff0000, v64
	v_lshlrev_b32_e32 v37, 16, v64
	v_lshlrev_b32_e32 v36, 16, v60
	v_pk_mul_f32 v[38:39], v[4:5], v[38:39]
	v_and_b32_e32 v30, 0xffff0000, v61
	v_pk_fma_f32 v[36:37], v[2:3], v[36:37], v[38:39]
	v_lshlrev_b32_e32 v39, 16, v65
	v_lshlrev_b32_e32 v38, 16, v61
	v_pk_fma_f32 v[36:37], v[6:7], v[38:39], v[36:37]
	v_and_b32_e32 v31, 0xffff0000, v65
	v_pk_fma_f32 v[26:27], v[8:9], v[30:31], v[36:37]
	v_lshlrev_b32_e32 v31, 16, v66
	v_lshlrev_b32_e32 v30, 16, v62
	v_pk_fma_f32 v[26:27], v[10:11], v[30:31], v[26:27]
	v_and_b32_e32 v31, 0xffff0000, v66
	v_and_b32_e32 v30, 0xffff0000, v62
	v_pk_fma_f32 v[26:27], v[12:13], v[30:31], v[26:27]
	v_lshlrev_b32_e32 v31, 16, v67
	v_lshlrev_b32_e32 v30, 16, v63
	v_pk_fma_f32 v[26:27], v[14:15], v[30:31], v[26:27]
	v_and_b32_e32 v31, 0xffff0000, v67
	v_and_b32_e32 v30, 0xffff0000, v63
	v_pk_fma_f32 v[26:27], v[16:17], v[30:31], v[26:27]
	s_nop 0
	v_add_f32_e32 v23, v22, v26
	v_add_f32_e32 v23, v23, v27
	v_min_f32_e32 v25, 0, v23
	v_mul_f32_e64 v23, |v23|, s95
	v_exp_f32_e32 v23, v23
	s_nop 0
	v_add_f32_e32 v23, 1.0, v23
	v_cmp_gt_f32_e32 vcc, s34, v23
	s_nop 1
	v_cndmask_b32_e64 v26, 0, 32, vcc
	v_ldexp_f32 v23, v23, v26
	v_log_f32_e32 v23, v23
	s_nop 0
	v_mul_f32_e32 v26, 0x3f317217, v23
	v_fma_f32 v26, v23, s35, -v26
	v_fmac_f32_e32 v26, 0x3377d1cf, v23
	v_fmac_f32_e32 v26, 0x3f317217, v23
	v_cmp_lt_f32_e64 s[0:1], |v23|, s73
	s_nop 1
	v_cndmask_b32_e64 v23, v23, v26, s[0:1]
	v_cndmask_b32_e32 v26, 0, v210, vcc
	v_sub_f32_e32 v23, v23, v26
	v_sub_f32_e32 v23, v25, v23
	v_mul_f32_e32 v29, 0x3d800000, v23
	global_load_dwordx4 v[60:63], v[32:33], off
	global_load_dwordx4 v[64:67], v[32:33], off offset:16
	v_lshl_add_u64 v[32:33], v[32:33], 0, s[10:11]
	ds_write2st64_b32 v0, v28, v29 offset1:4
	s_waitcnt vmcnt(24)
; __device__ __forceinline__ float logsigmoidf(float x) { return fminf(x, 0.f) - __logf(1.f + __expf(-fabsf(x))); }
; __device__ __forceinline__ void build_cum(const Args& a, int L, int hl, long R0, const bf16_t* __restrict__ proj, LAS unsigned char* lds) {
;     ...
;         for (int it = 0; it < 16; ++it) { const int i = isub + 4 * it; const bf16_t* ga = proj + (R0 + i) * LD + GAF + dir * 16;
;             const u32x4 g0 = *(const u32x4*)ga, g1 = *(const u32x4*)(ga + 8);
;             float x = gb;
;             x += gw[0] * bflo(g0.x) + gw[1] * bfhi(g0.x) + gw[2] * bflo(g0.y) + gw[3] * bfhi(g0.y) + gw[4] * bflo(g0.z) + gw[5] * bfhi(g0.z) + gw[6] * bflo(g0.w) + gw[7] * bfhi(g0.w);
;             x += gw[8] * bflo(g1.x) + gw[9] * bfhi(g1.x) + gw[10] * bflo(g1.y) + gw[11] * bfhi(g1.y) + gw[12] * bflo(g1.z) + gw[13] * bfhi(g1.z) + gw[14] * bflo(g1.w) + gw[15] * bfhi(g1.w);
;             cum[(dir * 64 + i) * 64 + k] = logsigmoidf(x) * (1.0f / 16.0f); }
	v_and_b32_e32 v38, 0xffff0000, v68
	v_and_b32_e32 v39, 0xffff0000, v72
	v_lshlrev_b32_e32 v37, 16, v72
	v_lshlrev_b32_e32 v36, 16, v68
	v_pk_mul_f32 v[38:39], v[4:5], v[38:39]
	v_and_b32_e32 v30, 0xffff0000, v69
	v_pk_fma_f32 v[36:37], v[2:3], v[36:37], v[38:39]
	v_lshlrev_b32_e32 v39, 16, v73
	v_lshlrev_b32_e32 v38, 16, v69
	v_pk_fma_f32 v[36:37], v[6:7], v[38:39], v[36:37]
	v_and_b32_e32 v31, 0xffff0000, v73
	v_pk_fma_f32 v[26:27], v[8:9], v[30:31], v[36:37]
	v_lshlrev_b32_e32 v31, 16, v74
	v_lshlrev_b32_e32 v30, 16, v70
	v_pk_fma_f32 v[26:27], v[10:11], v[30:31], v[26:27]
	v_and_b32_e32 v31, 0xffff0000, v74
	v_and_b32_e32 v30, 0xffff0000, v70
	v_pk_fma_f32 v[26:27], v[12:13], v[30:31], v[26:27]
	v_lshlrev_b32_e32 v31, 16, v75
	v_lshlrev_b32_e32 v30, 16, v71
	v_pk_fma_f32 v[26:27], v[14:15], v[30:31], v[26:27]
	v_and_b32_e32 v31, 0xffff0000, v75
	v_and_b32_e32 v30, 0xffff0000, v71
	v_pk_fma_f32 v[26:27], v[16:17], v[30:31], v[26:27]
	s_nop 0
	v_add_f32_e32 v23, v22, v26
	v_add_f32_e32 v23, v23, v27
	v_min_f32_e32 v25, 0, v23
	v_mul_f32_e64 v23, |v23|, s95
	v_exp_f32_e32 v23, v23
	s_nop 0
	v_add_f32_e32 v23, 1.0, v23
	v_cmp_gt_f32_e32 vcc, s34, v23
	s_nop 1
	v_cndmask_b32_e64 v26, 0, 32, vcc
	v_ldexp_f32 v23, v23, v26
	v_log_f32_e32 v23, v23
	s_nop 0
	v_mul_f32_e32 v26, 0x3f317217, v23
	v_fma_f32 v26, v23, s35, -v26
	v_fmac_f32_e32 v26, 0x3377d1cf, v23
	v_fmac_f32_e32 v26, 0x3f317217, v23
	v_cmp_lt_f32_e64 s[0:1], |v23|, s73
	s_nop 1
	v_cndmask_b32_e64 v23, v23, v26, s[0:1]
	v_cndmask_b32_e32 v26, 0, v210, vcc
	v_sub_f32_e32 v23, v23, v26
	v_sub_f32_e32 v23, v25, v23
	v_mul_f32_e32 v28, 0x3d800000, v23
	global_load_dwordx4 v[68:71], v[32:33], off
	global_load_dwordx4 v[72:75], v[32:33], off offset:16
	v_lshl_add_u64 v[32:33], v[32:33], 0, s[10:11]
	s_waitcnt vmcnt(24)
	v_and_b32_e32 v38, 0xffff0000, v76
	v_and_b32_e32 v39, 0xffff0000, v80
	v_lshlrev_b32_e32 v37, 16, v80
	v_lshlrev_b32_e32 v36, 16, v76
	v_pk_mul_f32 v[38:39], v[4:5], v[38:39]
	v_and_b32_e32 v30, 0xffff0000, v77
	v_pk_fma_f32 v[36:37], v[2:3], v[36:37], v[38:39]
	v_lshlrev_b32_e32 v39, 16, v81
	v_lshlrev_b32_e32 v38, 16, v77
	v_pk_fma_f32 v[36:37], v[6:7], v[38:39], v[36:37]
	v_and_b32_e32 v31, 0xffff0000, v81
	v_pk_fma_f32 v[26:27], v[8:9], v[30:31], v[36:37]
	v_lshlrev_b32_e32 v31, 16, v82
	v_lshlrev_b32_e32 v30, 16, v78
	v_pk_fma_f32 v[26:27], v[10:11], v[30:31], v[26:27]
	v_and_b32_e32 v31, 0xffff0000, v82
	v_and_b32_e32 v30, 0xffff0000, v78
	v_pk_fma_f32 v[26:27], v[12:13], v[30:31], v[26:27]
	v_lshlrev_b32_e32 v31, 16, v83
	v_lshlrev_b32_e32 v30, 16, v79
	v_pk_fma_f32 v[26:27], v[14:15], v[30:31], v[26:27]
	v_and_b32_e32 v31, 0xffff0000, v83
	v_and_b32_e32 v30, 0xffff0000, v79
	v_pk_fma_f32 v[26:27], v[16:17], v[30:31], v[26:27]
	s_nop 0
	v_add_f32_e32 v23, v22, v26
	v_add_f32_e32 v23, v23, v27
	v_min_f32_e32 v25, 0, v23
	v_mul_f32_e64 v23, |v23|, s95
	v_exp_f32_e32 v23, v23
	s_nop 0
	v_add_f32_e32 v23, 1.0, v23
	v_cmp_gt_f32_e32 vcc, s34, v23
	s_nop 1
	v_cndmask_b32_e64 v26, 0, 32, vcc
	v_ldexp_f32 v23, v23, v26
	v_log_f32_e32 v23, v23
	s_nop 0
	v_mul_f32_e32 v26, 0x3f317217, v23
	v_fma_f32 v26, v23, s35, -v26
	v_fmac_f32_e32 v26, 0x3377d1cf, v23
	v_fmac_f32_e32 v26, 0x3f317217, v23
	v_cmp_lt_f32_e64 s[0:1], |v23|, s73
	s_nop 1
	v_cndmask_b32_e64 v23, v23, v26, s[0:1]
	v_cndmask_b32_e32 v26, 0, v210, vcc
	v_sub_f32_e32 v23, v23, v26
	v_sub_f32_e32 v23, v25, v23
	v_mul_f32_e32 v29, 0x3d800000, v23
	ds_write2st64_b32 v0, v28, v29 offset0:8 offset1:12
	v_add_u32_e32 v0, 0x1000, v0
	s_waitcnt vmcnt(22)
	v_and_b32_e32 v38, 0xffff0000, v84
	v_and_b32_e32 v39, 0xffff0000, v88
	v_lshlrev_b32_e32 v37, 16, v88
	v_lshlrev_b32_e32 v36, 16, v84
	v_pk_mul_f32 v[38:39], v[4:5], v[38:39]
	v_and_b32_e32 v30, 0xffff0000, v85
	v_pk_fma_f32 v[36:37], v[2:3], v[36:37], v[38:39]
	v_lshlrev_b32_e32 v39, 16, v89
	v_lshlrev_b32_e32 v38, 16, v85
	v_pk_fma_f32 v[36:37], v[6:7], v[38:39], v[36:37]
	v_and_b32_e32 v31, 0xffff0000, v89
	v_pk_fma_f32 v[26:27], v[8:9], v[30:31], v[36:37]
	v_lshlrev_b32_e32 v31, 16, v90
	v_lshlrev_b32_e32 v30, 16, v86
	v_pk_fma_f32 v[26:27], v[10:11], v[30:31], v[26:27]
	v_and_b32_e32 v31, 0xffff0000, v90
	v_and_b32_e32 v30, 0xffff0000, v86
	v_pk_fma_f32 v[26:27], v[12:13], v[30:31], v[26:27]
	v_lshlrev_b32_e32 v31, 16, v91
	v_lshlrev_b32_e32 v30, 16, v87
	v_pk_fma_f32 v[26:27], v[14:15], v[30:31], v[26:27]
	v_and_b32_e32 v31, 0xffff0000, v91
	v_and_b32_e32 v30, 0xffff0000, v87
	v_pk_fma_f32 v[26:27], v[16:17], v[30:31], v[26:27]
	s_nop 0
	v_add_f32_e32 v23, v22, v26
	v_add_f32_e32 v23, v23, v27
	v_min_f32_e32 v25, 0, v23
	v_mul_f32_e64 v23, |v23|, s95
	v_exp_f32_e32 v23, v23
	s_nop 0
	v_add_f32_e32 v23, 1.0, v23
	v_cmp_gt_f32_e32 vcc, s34, v23
	s_nop 1
	v_cndmask_b32_e64 v26, 0, 32, vcc
	v_ldexp_f32 v23, v23, v26
	v_log_f32_e32 v23, v23
	s_nop 0
	v_mul_f32_e32 v26, 0x3f317217, v23
	v_fma_f32 v26, v23, s35, -v26
	v_fmac_f32_e32 v26, 0x3377d1cf, v23
	v_fmac_f32_e32 v26, 0x3f317217, v23
	v_cmp_lt_f32_e64 s[0:1], |v23|, s73
	s_nop 1
	v_cndmask_b32_e64 v23, v23, v26, s[0:1]
	v_cndmask_b32_e32 v26, 0, v210, vcc
	v_sub_f32_e32 v23, v23, v26
	v_sub_f32_e32 v23, v25, v23
	v_mul_f32_e32 v28, 0x3d800000, v23
	s_waitcnt vmcnt(20)
; __device__ __forceinline__ float logsigmoidf(float x) { return fminf(x, 0.f) - __logf(1.f + __expf(-fabsf(x))); }
; __device__ __forceinline__ void build_cum(const Args& a, int L, int hl, long R0, const bf16_t* __restrict__ proj, LAS unsigned char* lds) {
;     ...
;         for (int it = 0; it < 16; ++it) { const int i = isub + 4 * it; const bf16_t* ga = proj + (R0 + i) * LD + GAF + dir * 16;
;             const u32x4 g0 = *(const u32x4*)ga, g1 = *(const u32x4*)(ga + 8);
;             float x = gb;
;             x += gw[0] * bflo(g0.x) + gw[1] * bfhi(g0.x) + gw[2] * bflo(g0.y) + gw[3] * bfhi(g0.y) + gw[4] * bflo(g0.z) + gw[5] * bfhi(g0.z) + gw[6] * bflo(g0.w) + gw[7] * bfhi(g0.w);
;             x += gw[8] * bflo(g1.x) + gw[9] * bfhi(g1.x) + gw[10] * bflo(g1.y) + gw[11] * bfhi(g1.y) + gw[12] * bflo(g1.z) + gw[13] * bfhi(g1.z) + gw[14] * bflo(g1.w) + gw[15] * bfhi(g1.w);
;             cum[(dir * 64 + i) * 64 + k] = logsigmoidf(x) * (1.0f / 16.0f); }
	v_and_b32_e32 v38, 0xffff0000, v92
	v_and_b32_e32 v39, 0xffff0000, v96
	v_lshlrev_b32_e32 v37, 16, v96
	v_lshlrev_b32_e32 v36, 16, v92
	v_pk_mul_f32 v[38:39], v[4:5], v[38:39]
	v_and_b32_e32 v30, 0xffff0000, v93
	v_pk_fma_f32 v[36:37], v[2:3], v[36:37], v[38:39]
	v_lshlrev_b32_e32 v39, 16, v97
	v_lshlrev_b32_e32 v38, 16, v93
	v_pk_fma_f32 v[36:37], v[6:7], v[38:39], v[36:37]
	v_and_b32_e32 v31, 0xffff0000, v97
	v_pk_fma_f32 v[26:27], v[8:9], v[30:31], v[36:37]
	v_lshlrev_b32_e32 v31, 16, v98
	v_lshlrev_b32_e32 v30, 16, v94
	v_pk_fma_f32 v[26:27], v[10:11], v[30:31], v[26:27]
	v_and_b32_e32 v31, 0xffff0000, v98
	v_and_b32_e32 v30, 0xffff0000, v94
	v_pk_fma_f32 v[26:27], v[12:13], v[30:31], v[26:27]
	v_lshlrev_b32_e32 v31, 16, v99
	v_lshlrev_b32_e32 v30, 16, v95
	v_pk_fma_f32 v[26:27], v[14:15], v[30:31], v[26:27]
	v_and_b32_e32 v31, 0xffff0000, v99
	v_and_b32_e32 v30, 0xffff0000, v95
	v_pk_fma_f32 v[26:27], v[16:17], v[30:31], v[26:27]
	s_nop 0
	v_add_f32_e32 v23, v22, v26
	v_add_f32_e32 v23, v23, v27
	v_min_f32_e32 v25, 0, v23
	v_mul_f32_e64 v23, |v23|, s95
	v_exp_f32_e32 v23, v23
	s_nop 0
	v_add_f32_e32 v23, 1.0, v23
	v_cmp_gt_f32_e32 vcc, s34, v23
	s_nop 1
	v_cndmask_b32_e64 v26, 0, 32, vcc
	v_ldexp_f32 v23, v23, v26
	v_log_f32_e32 v23, v23
	s_nop 0
	v_mul_f32_e32 v26, 0x3f317217, v23
	v_fma_f32 v26, v23, s35, -v26
	v_fmac_f32_e32 v26, 0x3377d1cf, v23
	v_fmac_f32_e32 v26, 0x3f317217, v23
	v_cmp_lt_f32_e64 s[0:1], |v23|, s73
	s_nop 1
	v_cndmask_b32_e64 v23, v23, v26, s[0:1]
	v_cndmask_b32_e32 v26, 0, v210, vcc
	v_sub_f32_e32 v23, v23, v26
	v_sub_f32_e32 v23, v25, v23
	v_mul_f32_e32 v29, 0x3d800000, v23
	ds_write2st64_b32 v0, v28, v29 offset1:4
	s_waitcnt vmcnt(18)
	v_and_b32_e32 v38, 0xffff0000, v100
	v_and_b32_e32 v39, 0xffff0000, v104
	v_lshlrev_b32_e32 v37, 16, v104
	v_lshlrev_b32_e32 v36, 16, v100
	v_pk_mul_f32 v[38:39], v[4:5], v[38:39]
	v_and_b32_e32 v30, 0xffff0000, v101
	v_pk_fma_f32 v[36:37], v[2:3], v[36:37], v[38:39]
	v_lshlrev_b32_e32 v39, 16, v105
	v_lshlrev_b32_e32 v38, 16, v101
	v_pk_fma_f32 v[36:37], v[6:7], v[38:39], v[36:37]
	v_and_b32_e32 v31, 0xffff0000, v105
	v_pk_fma_f32 v[26:27], v[8:9], v[30:31], v[36:37]
	v_lshlrev_b32_e32 v31, 16, v106
	v_lshlrev_b32_e32 v30, 16, v102
	v_pk_fma_f32 v[26:27], v[10:11], v[30:31], v[26:27]
	v_and_b32_e32 v31, 0xffff0000, v106
	v_and_b32_e32 v30, 0xffff0000, v102
	v_pk_fma_f32 v[26:27], v[12:13], v[30:31], v[26:27]
	v_lshlrev_b32_e32 v31, 16, v107
	v_lshlrev_b32_e32 v30, 16, v103
	v_pk_fma_f32 v[26:27], v[14:15], v[30:31], v[26:27]
	v_and_b32_e32 v31, 0xffff0000, v107
	v_and_b32_e32 v30, 0xffff0000, v103
	v_pk_fma_f32 v[26:27], v[16:17], v[30:31], v[26:27]
	s_nop 0
	v_add_f32_e32 v23, v22, v26
	v_add_f32_e32 v23, v23, v27
	v_min_f32_e32 v25, 0, v23
	v_mul_f32_e64 v23, |v23|, s95
	v_exp_f32_e32 v23, v23
	s_nop 0
	v_add_f32_e32 v23, 1.0, v23
	v_cmp_gt_f32_e32 vcc, s34, v23
	s_nop 1
	v_cndmask_b32_e64 v26, 0, 32, vcc
	v_ldexp_f32 v23, v23, v26
	v_log_f32_e32 v23, v23
	s_nop 0
	v_mul_f32_e32 v26, 0x3f317217, v23
	v_fma_f32 v26, v23, s35, -v26
	v_fmac_f32_e32 v26, 0x3377d1cf, v23
	v_fmac_f32_e32 v26, 0x3f317217, v23
	v_cmp_lt_f32_e64 s[0:1], |v23|, s73
	s_nop 1
	v_cndmask_b32_e64 v23, v23, v26, s[0:1]
	v_cndmask_b32_e32 v26, 0, v210, vcc
	v_sub_f32_e32 v23, v23, v26
	v_sub_f32_e32 v23, v25, v23
	v_mul_f32_e32 v28, 0x3d800000, v23
	s_waitcnt vmcnt(16)
	v_and_b32_e32 v38, 0xffff0000, v108
	v_and_b32_e32 v39, 0xffff0000, v112
	v_lshlrev_b32_e32 v37, 16, v112
	v_lshlrev_b32_e32 v36, 16, v108
	v_pk_mul_f32 v[38:39], v[4:5], v[38:39]
	v_and_b32_e32 v30, 0xffff0000, v109
	v_pk_fma_f32 v[36:37], v[2:3], v[36:37], v[38:39]
	v_lshlrev_b32_e32 v39, 16, v113
	v_lshlrev_b32_e32 v38, 16, v109
	v_pk_fma_f32 v[36:37], v[6:7], v[38:39], v[36:37]
	v_and_b32_e32 v31, 0xffff0000, v113
	v_pk_fma_f32 v[26:27], v[8:9], v[30:31], v[36:37]
	v_lshlrev_b32_e32 v31, 16, v114
	v_lshlrev_b32_e32 v30, 16, v110
	v_pk_fma_f32 v[26:27], v[10:11], v[30:31], v[26:27]
	v_and_b32_e32 v31, 0xffff0000, v114
	v_and_b32_e32 v30, 0xffff0000, v110
	v_pk_fma_f32 v[26:27], v[12:13], v[30:31], v[26:27]
	v_lshlrev_b32_e32 v31, 16, v115
	v_lshlrev_b32_e32 v30, 16, v111
	v_pk_fma_f32 v[26:27], v[14:15], v[30:31], v[26:27]
	v_and_b32_e32 v31, 0xffff0000, v115
	v_and_b32_e32 v30, 0xffff0000, v111
	v_pk_fma_f32 v[26:27], v[16:17], v[30:31], v[26:27]
	s_nop 0
	v_add_f32_e32 v23, v22, v26
	v_add_f32_e32 v23, v23, v27
	v_min_f32_e32 v25, 0, v23
	v_mul_f32_e64 v23, |v23|, s95
	v_exp_f32_e32 v23, v23
	s_nop 0
	v_add_f32_e32 v23, 1.0, v23
	v_cmp_gt_f32_e32 vcc, s34, v23
	s_nop 1
	v_cndmask_b32_e64 v26, 0, 32, vcc
	v_ldexp_f32 v23, v23, v26
	v_log_f32_e32 v23, v23
	s_nop 0
	v_mul_f32_e32 v26, 0x3f317217, v23
	v_fma_f32 v26, v23, s35, -v26
	v_fmac_f32_e32 v26, 0x3377d1cf, v23
	v_fmac_f32_e32 v26, 0x3f317217, v23
	v_cmp_lt_f32_e64 s[0:1], |v23|, s73
	s_nop 1
	v_cndmask_b32_e64 v23, v23, v26, s[0:1]
	v_cndmask_b32_e32 v26, 0, v210, vcc
	v_sub_f32_e32 v23, v23, v26
	v_sub_f32_e32 v23, v25, v23
	v_mul_f32_e32 v29, 0x3d800000, v23
	ds_write2st64_b32 v0, v28, v29 offset0:8 offset1:12
	v_add_u32_e32 v0, 0x1000, v0
	s_waitcnt vmcnt(14)
; __device__ __forceinline__ float logsigmoidf(float x) { return fminf(x, 0.f) - __logf(1.f + __expf(-fabsf(x))); }
; __device__ __forceinline__ void build_cum(const Args& a, int L, int hl, long R0, const bf16_t* __restrict__ proj, LAS unsigned char* lds) {
;     ...
;         for (int it = 0; it < 16; ++it) { const int i = isub + 4 * it; const bf16_t* ga = proj + (R0 + i) * LD + GAF + dir * 16;
;             const u32x4 g0 = *(const u32x4*)ga, g1 = *(const u32x4*)(ga + 8);
;             float x = gb;
;             x += gw[0] * bflo(g0.x) + gw[1] * bfhi(g0.x) + gw[2] * bflo(g0.y) + gw[3] * bfhi(g0.y) + gw[4] * bflo(g0.z) + gw[5] * bfhi(g0.z) + gw[6] * bflo(g0.w) + gw[7] * bfhi(g0.w);
;             x += gw[8] * bflo(g1.x) + gw[9] * bfhi(g1.x) + gw[10] * bflo(g1.y) + gw[11] * bfhi(g1.y) + gw[12] * bflo(g1.z) + gw[13] * bfhi(g1.z) + gw[14] * bflo(g1.w) + gw[15] * bfhi(g1.w);
;             cum[(dir * 64 + i) * 64 + k] = logsigmoidf(x) * (1.0f / 16.0f); }
	v_and_b32_e32 v38, 0xffff0000, v116
	v_and_b32_e32 v39, 0xffff0000, v120
	v_lshlrev_b32_e32 v37, 16, v120
	v_lshlrev_b32_e32 v36, 16, v116
	v_pk_mul_f32 v[38:39], v[4:5], v[38:39]
	v_and_b32_e32 v30, 0xffff0000, v117
	v_pk_fma_f32 v[36:37], v[2:3], v[36:37], v[38:39]
	v_lshlrev_b32_e32 v39, 16, v121
	v_lshlrev_b32_e32 v38, 16, v117
	v_pk_fma_f32 v[36:37], v[6:7], v[38:39], v[36:37]
	v_and_b32_e32 v31, 0xffff0000, v121
	v_pk_fma_f32 v[26:27], v[8:9], v[30:31], v[36:37]
	v_lshlrev_b32_e32 v31, 16, v122
	v_lshlrev_b32_e32 v30, 16, v118
	v_pk_fma_f32 v[26:27], v[10:11], v[30:31], v[26:27]
	v_and_b32_e32 v31, 0xffff0000, v122
	v_and_b32_e32 v30, 0xffff0000, v118
	v_pk_fma_f32 v[26:27], v[12:13], v[30:31], v[26:27]
	v_lshlrev_b32_e32 v31, 16, v123
	v_lshlrev_b32_e32 v30, 16, v119
	v_pk_fma_f32 v[26:27], v[14:15], v[30:31], v[26:27]
	v_and_b32_e32 v31, 0xffff0000, v123
	v_and_b32_e32 v30, 0xffff0000, v119
	v_pk_fma_f32 v[26:27], v[16:17], v[30:31], v[26:27]
	s_nop 0
	v_add_f32_e32 v23, v22, v26
	v_add_f32_e32 v23, v23, v27
	v_min_f32_e32 v25, 0, v23
	v_mul_f32_e64 v23, |v23|, s95
	v_exp_f32_e32 v23, v23
	s_nop 0
	v_add_f32_e32 v23, 1.0, v23
	v_cmp_gt_f32_e32 vcc, s34, v23
	s_nop 1
	v_cndmask_b32_e64 v26, 0, 32, vcc
	v_ldexp_f32 v23, v23, v26
	v_log_f32_e32 v23, v23
	s_nop 0
	v_mul_f32_e32 v26, 0x3f317217, v23
	v_fma_f32 v26, v23, s35, -v26
	v_fmac_f32_e32 v26, 0x3377d1cf, v23
	v_fmac_f32_e32 v26, 0x3f317217, v23
	v_cmp_lt_f32_e64 s[0:1], |v23|, s73
	s_nop 1
	v_cndmask_b32_e64 v23, v23, v26, s[0:1]
	v_cndmask_b32_e32 v26, 0, v210, vcc
	v_sub_f32_e32 v23, v23, v26
	v_sub_f32_e32 v23, v25, v23
	v_mul_f32_e32 v28, 0x3d800000, v23
	s_waitcnt vmcnt(12)
	v_and_b32_e32 v38, 0xffff0000, v124
	v_and_b32_e32 v39, 0xffff0000, v128
	v_lshlrev_b32_e32 v37, 16, v128
	v_lshlrev_b32_e32 v36, 16, v124
	v_pk_mul_f32 v[38:39], v[4:5], v[38:39]
	v_and_b32_e32 v30, 0xffff0000, v125
	v_pk_fma_f32 v[36:37], v[2:3], v[36:37], v[38:39]
	v_lshlrev_b32_e32 v39, 16, v129
	v_lshlrev_b32_e32 v38, 16, v125
	v_pk_fma_f32 v[36:37], v[6:7], v[38:39], v[36:37]
	v_and_b32_e32 v31, 0xffff0000, v129
	v_pk_fma_f32 v[26:27], v[8:9], v[30:31], v[36:37]
	v_lshlrev_b32_e32 v31, 16, v130
	v_lshlrev_b32_e32 v30, 16, v126
	v_pk_fma_f32 v[26:27], v[10:11], v[30:31], v[26:27]
	v_and_b32_e32 v31, 0xffff0000, v130
	v_and_b32_e32 v30, 0xffff0000, v126
	v_pk_fma_f32 v[26:27], v[12:13], v[30:31], v[26:27]
	v_lshlrev_b32_e32 v31, 16, v131
	v_lshlrev_b32_e32 v30, 16, v127
	v_pk_fma_f32 v[26:27], v[14:15], v[30:31], v[26:27]
	v_and_b32_e32 v31, 0xffff0000, v131
	v_and_b32_e32 v30, 0xffff0000, v127
	v_pk_fma_f32 v[26:27], v[16:17], v[30:31], v[26:27]
	s_nop 0
	v_add_f32_e32 v23, v22, v26
	v_add_f32_e32 v23, v23, v27
	v_min_f32_e32 v25, 0, v23
	v_mul_f32_e64 v23, |v23|, s95
	v_exp_f32_e32 v23, v23
	s_nop 0
	v_add_f32_e32 v23, 1.0, v23
	v_cmp_gt_f32_e32 vcc, s34, v23
	s_nop 1
	v_cndmask_b32_e64 v26, 0, 32, vcc
	v_ldexp_f32 v23, v23, v26
	v_log_f32_e32 v23, v23
	s_nop 0
	v_mul_f32_e32 v26, 0x3f317217, v23
	v_fma_f32 v26, v23, s35, -v26
	v_fmac_f32_e32 v26, 0x3377d1cf, v23
	v_fmac_f32_e32 v26, 0x3f317217, v23
	v_cmp_lt_f32_e64 s[0:1], |v23|, s73
	s_nop 1
	v_cndmask_b32_e64 v23, v23, v26, s[0:1]
	v_cndmask_b32_e32 v26, 0, v210, vcc
	v_sub_f32_e32 v23, v23, v26
	v_sub_f32_e32 v23, v25, v23
	v_mul_f32_e32 v29, 0x3d800000, v23
	ds_write2st64_b32 v0, v28, v29 offset1:4
	s_waitcnt vmcnt(10)
	v_and_b32_e32 v38, 0xffff0000, v132
	v_and_b32_e32 v39, 0xffff0000, v136
	v_lshlrev_b32_e32 v37, 16, v136
	v_lshlrev_b32_e32 v36, 16, v132
	v_pk_mul_f32 v[38:39], v[4:5], v[38:39]
	v_and_b32_e32 v30, 0xffff0000, v133
	v_pk_fma_f32 v[36:37], v[2:3], v[36:37], v[38:39]
	v_lshlrev_b32_e32 v39, 16, v137
	v_lshlrev_b32_e32 v38, 16, v133
	v_pk_fma_f32 v[36:37], v[6:7], v[38:39], v[36:37]
	v_and_b32_e32 v31, 0xffff0000, v137
	v_pk_fma_f32 v[26:27], v[8:9], v[30:31], v[36:37]
	v_lshlrev_b32_e32 v31, 16, v138
	v_lshlrev_b32_e32 v30, 16, v134
	v_pk_fma_f32 v[26:27], v[10:11], v[30:31], v[26:27]
	v_and_b32_e32 v31, 0xffff0000, v138
	v_and_b32_e32 v30, 0xffff0000, v134
	v_pk_fma_f32 v[26:27], v[12:13], v[30:31], v[26:27]
	v_lshlrev_b32_e32 v31, 16, v139
	v_lshlrev_b32_e32 v30, 16, v135
	v_pk_fma_f32 v[26:27], v[14:15], v[30:31], v[26:27]
	v_and_b32_e32 v31, 0xffff0000, v139
	v_and_b32_e32 v30, 0xffff0000, v135
	v_pk_fma_f32 v[26:27], v[16:17], v[30:31], v[26:27]
	s_nop 0
	v_add_f32_e32 v23, v22, v26
	v_add_f32_e32 v23, v23, v27
	v_min_f32_e32 v25, 0, v23
	v_mul_f32_e64 v23, |v23|, s95
	v_exp_f32_e32 v23, v23
	s_nop 0
	v_add_f32_e32 v23, 1.0, v23
	v_cmp_gt_f32_e32 vcc, s34, v23
	s_nop 1
	v_cndmask_b32_e64 v26, 0, 32, vcc
	v_ldexp_f32 v23, v23, v26
	v_log_f32_e32 v23, v23
	s_nop 0
	v_mul_f32_e32 v26, 0x3f317217, v23
	v_fma_f32 v26, v23, s35, -v26
	v_fmac_f32_e32 v26, 0x3377d1cf, v23
	v_fmac_f32_e32 v26, 0x3f317217, v23
	v_cmp_lt_f32_e64 s[0:1], |v23|, s73
	s_nop 1
	v_cndmask_b32_e64 v23, v23, v26, s[0:1]
	v_cndmask_b32_e32 v26, 0, v210, vcc
	v_sub_f32_e32 v23, v23, v26
	v_sub_f32_e32 v23, v25, v23
	v_mul_f32_e32 v28, 0x3d800000, v23
	s_waitcnt vmcnt(8)
; __device__ __forceinline__ float logsigmoidf(float x) { return fminf(x, 0.f) - __logf(1.f + __expf(-fabsf(x))); }
; __device__ __forceinline__ void build_cum(const Args& a, int L, int hl, long R0, const bf16_t* __restrict__ proj, LAS unsigned char* lds) {
;     ...
;         for (int it = 0; it < 16; ++it) { const int i = isub + 4 * it; const bf16_t* ga = proj + (R0 + i) * LD + GAF + dir * 16;
;             const u32x4 g0 = *(const u32x4*)ga, g1 = *(const u32x4*)(ga + 8);
;             float x = gb;
;             x += gw[0] * bflo(g0.x) + gw[1] * bfhi(g0.x) + gw[2] * bflo(g0.y) + gw[3] * bfhi(g0.y) + gw[4] * bflo(g0.z) + gw[5] * bfhi(g0.z) + gw[6] * bflo(g0.w) + gw[7] * bfhi(g0.w);
;             x += gw[8] * bflo(g1.x) + gw[9] * bfhi(g1.x) + gw[10] * bflo(g1.y) + gw[11] * bfhi(g1.y) + gw[12] * bflo(g1.z) + gw[13] * bfhi(g1.z) + gw[14] * bflo(g1.w) + gw[15] * bfhi(g1.w);
;             cum[(dir * 64 + i) * 64 + k] = logsigmoidf(x) * (1.0f / 16.0f); }
	v_and_b32_e32 v38, 0xffff0000, v140
	v_and_b32_e32 v39, 0xffff0000, v144
	v_lshlrev_b32_e32 v37, 16, v144
	v_lshlrev_b32_e32 v36, 16, v140
	v_pk_mul_f32 v[38:39], v[4:5], v[38:39]
	v_and_b32_e32 v30, 0xffff0000, v141
	v_pk_fma_f32 v[36:37], v[2:3], v[36:37], v[38:39]
	v_lshlrev_b32_e32 v39, 16, v145
	v_lshlrev_b32_e32 v38, 16, v141
	v_pk_fma_f32 v[36:37], v[6:7], v[38:39], v[36:37]
	v_and_b32_e32 v31, 0xffff0000, v145
	v_pk_fma_f32 v[26:27], v[8:9], v[30:31], v[36:37]
	v_lshlrev_b32_e32 v31, 16, v146
	v_lshlrev_b32_e32 v30, 16, v142
	v_pk_fma_f32 v[26:27], v[10:11], v[30:31], v[26:27]
	v_and_b32_e32 v31, 0xffff0000, v146
	v_and_b32_e32 v30, 0xffff0000, v142
	v_pk_fma_f32 v[26:27], v[12:13], v[30:31], v[26:27]
	v_lshlrev_b32_e32 v31, 16, v147
	v_lshlrev_b32_e32 v30, 16, v143
	v_pk_fma_f32 v[26:27], v[14:15], v[30:31], v[26:27]
	v_and_b32_e32 v31, 0xffff0000, v147
	v_and_b32_e32 v30, 0xffff0000, v143
	v_pk_fma_f32 v[26:27], v[16:17], v[30:31], v[26:27]
	s_nop 0
	v_add_f32_e32 v23, v22, v26
	v_add_f32_e32 v23, v23, v27
	v_min_f32_e32 v25, 0, v23
	v_mul_f32_e64 v23, |v23|, s95
	v_exp_f32_e32 v23, v23
	s_nop 0
	v_add_f32_e32 v23, 1.0, v23
	v_cmp_gt_f32_e32 vcc, s34, v23
	s_nop 1
	v_cndmask_b32_e64 v26, 0, 32, vcc
	v_ldexp_f32 v23, v23, v26
	v_log_f32_e32 v23, v23
	s_nop 0
	v_mul_f32_e32 v26, 0x3f317217, v23
	v_fma_f32 v26, v23, s35, -v26
	v_fmac_f32_e32 v26, 0x3377d1cf, v23
	v_fmac_f32_e32 v26, 0x3f317217, v23
	v_cmp_lt_f32_e64 s[0:1], |v23|, s73
	s_nop 1
	v_cndmask_b32_e64 v23, v23, v26, s[0:1]
	v_cndmask_b32_e32 v26, 0, v210, vcc
	v_sub_f32_e32 v23, v23, v26
	v_sub_f32_e32 v23, v25, v23
	v_mul_f32_e32 v29, 0x3d800000, v23
	ds_write2st64_b32 v0, v28, v29 offset0:8 offset1:12
	v_add_u32_e32 v0, 0x1000, v0
	s_waitcnt vmcnt(6)
	v_and_b32_e32 v38, 0xffff0000, v148
	v_and_b32_e32 v39, 0xffff0000, v152
	v_lshlrev_b32_e32 v37, 16, v152
	v_lshlrev_b32_e32 v36, 16, v148
	v_pk_mul_f32 v[38:39], v[4:5], v[38:39]
	v_and_b32_e32 v30, 0xffff0000, v149
	v_pk_fma_f32 v[36:37], v[2:3], v[36:37], v[38:39]
	v_lshlrev_b32_e32 v39, 16, v153
	v_lshlrev_b32_e32 v38, 16, v149
	v_pk_fma_f32 v[36:37], v[6:7], v[38:39], v[36:37]
	v_and_b32_e32 v31, 0xffff0000, v153
	v_pk_fma_f32 v[26:27], v[8:9], v[30:31], v[36:37]
	v_lshlrev_b32_e32 v31, 16, v154
	v_lshlrev_b32_e32 v30, 16, v150
	v_pk_fma_f32 v[26:27], v[10:11], v[30:31], v[26:27]
	v_and_b32_e32 v31, 0xffff0000, v154
	v_and_b32_e32 v30, 0xffff0000, v150
	v_pk_fma_f32 v[26:27], v[12:13], v[30:31], v[26:27]
	v_lshlrev_b32_e32 v31, 16, v155
	v_lshlrev_b32_e32 v30, 16, v151
	v_pk_fma_f32 v[26:27], v[14:15], v[30:31], v[26:27]
	v_and_b32_e32 v31, 0xffff0000, v155
	v_and_b32_e32 v30, 0xffff0000, v151
	v_pk_fma_f32 v[26:27], v[16:17], v[30:31], v[26:27]
	s_nop 0
	v_add_f32_e32 v23, v22, v26
	v_add_f32_e32 v23, v23, v27
	v_min_f32_e32 v25, 0, v23
	v_mul_f32_e64 v23, |v23|, s95
	v_exp_f32_e32 v23, v23
	s_nop 0
	v_add_f32_e32 v23, 1.0, v23
	v_cmp_gt_f32_e32 vcc, s34, v23
	s_nop 1
	v_cndmask_b32_e64 v26, 0, 32, vcc
	v_ldexp_f32 v23, v23, v26
	v_log_f32_e32 v23, v23
	s_nop 0
	v_mul_f32_e32 v26, 0x3f317217, v23
	v_fma_f32 v26, v23, s35, -v26
	v_fmac_f32_e32 v26, 0x3377d1cf, v23
	v_fmac_f32_e32 v26, 0x3f317217, v23
	v_cmp_lt_f32_e64 s[0:1], |v23|, s73
	s_nop 1
	v_cndmask_b32_e64 v23, v23, v26, s[0:1]
	v_cndmask_b32_e32 v26, 0, v210, vcc
	v_sub_f32_e32 v23, v23, v26
	v_sub_f32_e32 v23, v25, v23
	v_mul_f32_e32 v28, 0x3d800000, v23
	s_waitcnt vmcnt(4)
; __device__ __forceinline__ float logsigmoidf(float x) { return fminf(x, 0.f) - __logf(1.f + __expf(-fabsf(x))); }
; __device__ __forceinline__ void build_cum(const Args& a, int L, int hl, long R0, const bf16_t* __restrict__ proj, LAS unsigned char* lds) {
;     ...
;         for (int it = 0; it < 16; ++it) { const int i = isub + 4 * it; const bf16_t* ga = proj + (R0 + i) * LD + GAF + dir * 16;
;             const u32x4 g0 = *(const u32x4*)ga, g1 = *(const u32x4*)(ga + 8);
;             float x = gb;
;             x += gw[0] * bflo(g0.x) + gw[1] * bfhi(g0.x) + gw[2] * bflo(g0.y) + gw[3] * bfhi(g0.y) + gw[4] * bflo(g0.z) + gw[5] * bfhi(g0.z) + gw[6] * bflo(g0.w) + gw[7] * bfhi(g0.w);
;             x += gw[8] * bflo(g1.x) + gw[9] * bfhi(g1.x) + gw[10] * bflo(g1.y) + gw[11] * bfhi(g1.y) + gw[12] * bflo(g1.z) + gw[13] * bfhi(g1.z) + gw[14] * bflo(g1.w) + gw[15] * bfhi(g1.w);
;             cum[(dir * 64 + i) * 64 + k] = logsigmoidf(x) * (1.0f / 16.0f); }
	v_and_b32_e32 v38, 0xffff0000, v52
	v_and_b32_e32 v39, 0xffff0000, v56
	v_lshlrev_b32_e32 v37, 16, v56
	v_lshlrev_b32_e32 v36, 16, v52
	v_pk_mul_f32 v[38:39], v[4:5], v[38:39]
	v_and_b32_e32 v30, 0xffff0000, v53
	v_pk_fma_f32 v[36:37], v[2:3], v[36:37], v[38:39]
	v_lshlrev_b32_e32 v39, 16, v57
	v_lshlrev_b32_e32 v38, 16, v53
	v_pk_fma_f32 v[36:37], v[6:7], v[38:39], v[36:37]
	v_and_b32_e32 v31, 0xffff0000, v57
	v_pk_fma_f32 v[26:27], v[8:9], v[30:31], v[36:37]
	v_lshlrev_b32_e32 v31, 16, v58
	v_lshlrev_b32_e32 v30, 16, v54
	v_pk_fma_f32 v[26:27], v[10:11], v[30:31], v[26:27]
	v_and_b32_e32 v31, 0xffff0000, v58
	v_and_b32_e32 v30, 0xffff0000, v54
	v_pk_fma_f32 v[26:27], v[12:13], v[30:31], v[26:27]
	v_lshlrev_b32_e32 v31, 16, v59
	v_lshlrev_b32_e32 v30, 16, v55
	v_pk_fma_f32 v[26:27], v[14:15], v[30:31], v[26:27]
	v_and_b32_e32 v31, 0xffff0000, v59
	v_and_b32_e32 v30, 0xffff0000, v55
	v_pk_fma_f32 v[26:27], v[16:17], v[30:31], v[26:27]
	s_nop 0
	v_add_f32_e32 v23, v22, v26
	v_add_f32_e32 v23, v23, v27
	v_min_f32_e32 v25, 0, v23
	v_mul_f32_e64 v23, |v23|, s95
	v_exp_f32_e32 v23, v23
	s_nop 0
	v_add_f32_e32 v23, 1.0, v23
	v_cmp_gt_f32_e32 vcc, s34, v23
	s_nop 1
	v_cndmask_b32_e64 v26, 0, 32, vcc
	v_ldexp_f32 v23, v23, v26
	v_log_f32_e32 v23, v23
	s_nop 0
	v_mul_f32_e32 v26, 0x3f317217, v23
	v_fma_f32 v26, v23, s35, -v26
	v_fmac_f32_e32 v26, 0x3377d1cf, v23
	v_fmac_f32_e32 v26, 0x3f317217, v23
	v_cmp_lt_f32_e64 s[0:1], |v23|, s73
	s_nop 1
	v_cndmask_b32_e64 v23, v23, v26, s[0:1]
	v_cndmask_b32_e32 v26, 0, v210, vcc
	v_sub_f32_e32 v23, v23, v26
	v_sub_f32_e32 v23, v25, v23
	v_mul_f32_e32 v29, 0x3d800000, v23
	ds_write2st64_b32 v0, v28, v29 offset1:4
	s_waitcnt vmcnt(2)
	v_and_b32_e32 v38, 0xffff0000, v60
	v_and_b32_e32 v39, 0xffff0000, v64
	v_lshlrev_b32_e32 v37, 16, v64
	v_lshlrev_b32_e32 v36, 16, v60
	v_pk_mul_f32 v[38:39], v[4:5], v[38:39]
	v_and_b32_e32 v30, 0xffff0000, v61
	v_pk_fma_f32 v[36:37], v[2:3], v[36:37], v[38:39]
	v_lshlrev_b32_e32 v39, 16, v65
	v_lshlrev_b32_e32 v38, 16, v61
	v_pk_fma_f32 v[36:37], v[6:7], v[38:39], v[36:37]
	v_and_b32_e32 v31, 0xffff0000, v65
	v_pk_fma_f32 v[26:27], v[8:9], v[30:31], v[36:37]
	v_lshlrev_b32_e32 v31, 16, v66
	v_lshlrev_b32_e32 v30, 16, v62
	v_pk_fma_f32 v[26:27], v[10:11], v[30:31], v[26:27]
	v_and_b32_e32 v31, 0xffff0000, v66
	v_and_b32_e32 v30, 0xffff0000, v62
	v_pk_fma_f32 v[26:27], v[12:13], v[30:31], v[26:27]
	v_lshlrev_b32_e32 v31, 16, v67
	v_lshlrev_b32_e32 v30, 16, v63
	v_pk_fma_f32 v[26:27], v[14:15], v[30:31], v[26:27]
	v_and_b32_e32 v31, 0xffff0000, v67
	v_and_b32_e32 v30, 0xffff0000, v63
	v_pk_fma_f32 v[26:27], v[16:17], v[30:31], v[26:27]
	s_nop 0
	v_add_f32_e32 v23, v22, v26
	v_add_f32_e32 v23, v23, v27
	v_min_f32_e32 v25, 0, v23
	v_mul_f32_e64 v23, |v23|, s95
	v_exp_f32_e32 v23, v23
	s_nop 0
	v_add_f32_e32 v23, 1.0, v23
	v_cmp_gt_f32_e32 vcc, s34, v23
	s_nop 1
	v_cndmask_b32_e64 v26, 0, 32, vcc
	v_ldexp_f32 v23, v23, v26
	v_log_f32_e32 v23, v23
	s_nop 0
	v_mul_f32_e32 v26, 0x3f317217, v23
	v_fma_f32 v26, v23, s35, -v26
	v_fmac_f32_e32 v26, 0x3377d1cf, v23
	v_fmac_f32_e32 v26, 0x3f317217, v23
	v_cmp_lt_f32_e64 s[0:1], |v23|, s73
	s_nop 1
	v_cndmask_b32_e64 v23, v23, v26, s[0:1]
	v_cndmask_b32_e32 v26, 0, v210, vcc
	v_sub_f32_e32 v23, v23, v26
	v_sub_f32_e32 v23, v25, v23
	v_mul_f32_e32 v28, 0x3d800000, v23
	s_waitcnt vmcnt(0)
	v_and_b32_e32 v38, 0xffff0000, v68
	v_and_b32_e32 v39, 0xffff0000, v72
	v_lshlrev_b32_e32 v37, 16, v72
	v_lshlrev_b32_e32 v36, 16, v68
	v_pk_mul_f32 v[38:39], v[4:5], v[38:39]
	v_and_b32_e32 v30, 0xffff0000, v69
	v_pk_fma_f32 v[36:37], v[2:3], v[36:37], v[38:39]
	v_lshlrev_b32_e32 v39, 16, v73
	v_lshlrev_b32_e32 v38, 16, v69
	v_pk_fma_f32 v[36:37], v[6:7], v[38:39], v[36:37]
	v_and_b32_e32 v31, 0xffff0000, v73
	v_pk_fma_f32 v[26:27], v[8:9], v[30:31], v[36:37]
	v_lshlrev_b32_e32 v31, 16, v74
	v_lshlrev_b32_e32 v30, 16, v70
	v_pk_fma_f32 v[26:27], v[10:11], v[30:31], v[26:27]
	v_and_b32_e32 v31, 0xffff0000, v74
	v_and_b32_e32 v30, 0xffff0000, v70
	v_pk_fma_f32 v[26:27], v[12:13], v[30:31], v[26:27]
	v_lshlrev_b32_e32 v31, 16, v75
	v_lshlrev_b32_e32 v30, 16, v71
	v_pk_fma_f32 v[26:27], v[14:15], v[30:31], v[26:27]
	v_and_b32_e32 v31, 0xffff0000, v75
	v_and_b32_e32 v30, 0xffff0000, v71
	v_pk_fma_f32 v[26:27], v[16:17], v[30:31], v[26:27]
	s_nop 0
	v_add_f32_e32 v23, v22, v26
	v_add_f32_e32 v23, v23, v27
	v_min_f32_e32 v25, 0, v23
	v_mul_f32_e64 v23, |v23|, s95
	v_exp_f32_e32 v23, v23
	s_nop 0
	v_add_f32_e32 v23, 1.0, v23
	v_cmp_gt_f32_e32 vcc, s34, v23
	s_nop 1
	v_cndmask_b32_e64 v26, 0, 32, vcc
	v_ldexp_f32 v23, v23, v26
	v_log_f32_e32 v23, v23
	s_nop 0
	v_mul_f32_e32 v26, 0x3f317217, v23
	v_fma_f32 v26, v23, s35, -v26
	v_fmac_f32_e32 v26, 0x3377d1cf, v23
	v_fmac_f32_e32 v26, 0x3f317217, v23
	v_cmp_lt_f32_e64 s[0:1], |v23|, s73
	s_nop 1
	v_cndmask_b32_e64 v23, v23, v26, s[0:1]
	v_cndmask_b32_e32 v26, 0, v210, vcc
	v_sub_f32_e32 v23, v23, v26
	v_sub_f32_e32 v23, v25, v23
	v_mul_f32_e32 v29, 0x3d800000, v23
	ds_write2st64_b32 v0, v28, v29 offset0:8 offset1:12
	v_add_u32_e32 v0, 0x1000, v0

; __device__ __forceinline__ unsigned f2bf(float f) { unsigned u = __builtin_bit_cast(unsigned, f); return (u + 0x7fffu + ((u >> 16) & 1u)) >> 16; }
; __device__ __forceinline__ void r1_item(const Args& a, int L, int item, LAS unsigned char* lds) {
;     ...
;     if (tid < 256) { const int i = (tid >> 2) & 63, g = tid & 3; const int kcol = hl < 4 ? GK + hl * 64 : RK + (hl - 4) * 64;
;         float va[8], vb[8]; load_qk16(a, proj + (R0 + i) * LD + kcol, hl, c * 64 + i, g, va, vb);
; #pragma unroll
;         for (int dir = 0; dir < 2; ++dir) { const int lastrow = dir == 0 ? 63 : 64;
; #pragma unroll
;             for (int e = 0; e < 8; ++e) { const int ka = g * 8 + e, kb = 32 + g * 8 + e;
;                 const float wa = __expf(cum[lastrow * 64 + ka] - cum[(dir * 64 + i) * 64 + ka]), wb = __expf(cum[lastrow * 64 + kb] - cum[(dir * 64 + i) * 64 + kb]);
;                 KeT[(dir * 64 + ka) * PT + i] = (bf16_t)f2bf(va[e] * wa); KeT[(dir * 64 + kb) * PT + i] = (bf16_t)f2bf(vb[e] * wb); } }
;     } else { const int t2 = tid - 256, j = t2 >> 2, vg = t2 & 3; const int vcol = hl < 4 ? GV + hl * 128 : RV + (hl - 4) * 128;
;         const bf16_t* vp = proj + (R0 + j) * LD + vcol + vg * 32;
; #pragma unroll
;         for (int q = 0; q < 4; ++q) { const u32x4 w = *(const u32x4*)(vp + q * 8); const int v0 = vg * 32 + q * 8;
;             VT[(v0 + 0) * PT + j] = (bf16_t)(w.x & 0xffff); VT[(v0 + 1) * PT + j] = (bf16_t)(w.x >> 16); VT[(v0 + 2) * PT + j] = (bf16_t)(w.y & 0xffff); VT[(v0 + 3) * PT + j] = (bf16_t)(w.y >> 16);
;             VT[(v0 + 4) * PT + j] = (bf16_t)(w.z & 0xffff); VT[(v0 + 5) * PT + j] = (bf16_t)(w.z >> 16); VT[(v0 + 6) * PT + j] = (bf16_t)(w.w & 0xffff); VT[(v0 + 7) * PT + j] = (bf16_t)(w.w >> 16); } }
.LBB0_172:
	s_or_b64 exec, exec, s[0:1]
	s_and_b32 s15, s13, 63
	s_lshl_b64 s[10:11], s[4:5], 12
	s_lshl_b32 s5, s15, 6
	s_movk_i32 s0, 0xff
	s_or_b32 s10, s10, s5
	v_cmp_lt_i32_e32 vcc, s0, v34
	s_waitcnt lgkmcnt(0)
	s_barrier
	v_lshlrev_b32_e32 v68, 6, v34
	s_lshl_b32 s100, s13, 15
	s_add_u32 s100, s98, s100
	s_addc_u32 s101, s99, 0
	s_add_u32 s100, s100, 0x24300000
	s_addc_u32 s101, s101, 0
	ds_read_b128 v[52:55], v68
	ds_read_b128 v[56:59], v68 offset:16
	ds_read_b128 v[60:63], v68 offset:32
	ds_read_b128 v[64:67], v68 offset:48
	s_waitcnt lgkmcnt(0)
	global_store_dwordx4 v68, v[52:55], s[100:101]
	global_store_dwordx4 v68, v[56:59], s[100:101] offset:16
	global_store_dwordx4 v68, v[60:63], s[100:101] offset:32
	global_store_dwordx4 v68, v[64:67], s[100:101] offset:48
	s_and_saveexec_b64 s[0:1], vcc
	s_xor_b64 s[0:1], exec, s[0:1]
	s_cbranch_execz .LBB0_174
	v_add_u32_e32 v0, 0xffffff00, v34
	v_lshrrev_b32_e32 v0, 2, v0
	s_lshl_b32 s24, s14, 7
	v_lshl_add_u64 v[2:3], s[10:11], 0, v[0:1]
	v_mov_b64_e32 v[4:5], s[22:23]
	s_or_b32 s30, s24, 0xe00
	s_addk_i32 s24, 0x1200
	v_mad_u64_u32 v[4:5], s[28:29], v2, s79, v[4:5]
	s_and_b64 s[28:29], s[8:9], exec
	v_mov_b32_e32 v2, v5
	s_cselect_b32 s24, s30, s24
	v_mad_u64_u32 v[2:3], s[28:29], v3, s79, v[2:3]
	v_mov_b32_e32 v5, v2
	s_lshl_b32 s24, s24, 1
	v_lshl_add_u64 v[2:3], v[4:5], 0, s[24:25]
	v_lshlrev_b32_e32 v4, 5, v34
	v_and_b32_e32 v8, 0x60, v4
	v_lshlrev_b32_e32 v4, 1, v8
	v_mov_b32_e32 v5, v1
	v_lshl_add_u64 v[6:7], v[2:3], 0, v[4:5]
	v_mul_u32_u24_e32 v2, 0x90, v8
	v_lshlrev_b32_e32 v0, 1, v0
	v_add3_u32 v0, 0, v2, v0
	v_mov_b32_e32 v2, v156
	v_mov_b32_e32 v3, v157
	v_mov_b32_e32 v4, v158
	v_mov_b32_e32 v5, v159
	s_waitcnt vmcnt(0) lgkmcnt(0)
	ds_write_b16 v0, v2 offset:32768
	ds_write_b16_d16_hi v0, v2 offset:32912
	ds_write_b16 v0, v3 offset:33056
	ds_write_b16_d16_hi v0, v3 offset:33200
	ds_write_b16 v0, v4 offset:33344
	ds_write_b16_d16_hi v0, v4 offset:33488
	ds_write_b16 v0, v5 offset:33632
	ds_write_b16_d16_hi v0, v5 offset:33776
	ds_write_b16 v0, v160 offset:33920
	ds_write_b16_d16_hi v0, v160 offset:34064
	ds_write_b16 v0, v161 offset:34208
	ds_write_b16_d16_hi v0, v161 offset:34352
	ds_write_b16 v0, v162 offset:34496
	ds_write_b16_d16_hi v0, v162 offset:34640
	ds_write_b16 v0, v163 offset:34784
	ds_write_b16_d16_hi v0, v163 offset:34928
	ds_write_b16 v0, v164 offset:35072
	ds_write_b16_d16_hi v0, v164 offset:35216
	ds_write_b16 v0, v165 offset:35360
	ds_write_b16_d16_hi v0, v165 offset:35504
	ds_write_b16 v0, v166 offset:35648
	ds_write_b16_d16_hi v0, v166 offset:35792
	ds_write_b16 v0, v167 offset:35936
	ds_write_b16_d16_hi v0, v167 offset:36080
	ds_write_b16 v0, v168 offset:36224
	ds_write_b16_d16_hi v0, v168 offset:36368
	ds_write_b16 v0, v169 offset:36512
	ds_write_b16_d16_hi v0, v169 offset:36656
	ds_write_b16 v0, v170 offset:36800
	ds_write_b16_d16_hi v0, v170 offset:36944
	ds_write_b16 v0, v171 offset:37088
	ds_write_b16_d16_hi v0, v171 offset:37232
.LBB0_174:
	s_andn2_saveexec_b64 s[0:1], s[0:1]
	s_cbranch_execz .LBB0_178
	s_lshl_b32 s24, s14, 6
	s_and_b64 s[8:9], s[8:9], exec
	v_bfe_u32 v2, v34, 2, 6
	s_movk_i32 s8, 0xd00
	s_cselect_b32 s8, s8, 0x1200
	v_or_b32_e32 v0, s10, v2
	v_mov_b64_e32 v[4:5], s[22:23]
	s_add_i32 s24, s8, s24
	s_mul_i32 s10, s11, 0x3200
	v_mad_u64_u32 v[4:5], s[8:9], v0, s79, v[4:5]
	v_lshlrev_b32_e32 v0, 3, v34
	v_add_u32_e32 v5, s10, v5
	s_lshl_b32 s24, s24, 1
	v_and_b32_e32 v29, 24, v0
	v_lshl_add_u64 v[4:5], v[4:5], 0, s[24:25]
	v_lshlrev_b32_e32 v0, 1, v29
	v_lshl_add_u64 v[8:9], v[4:5], 0, v[0:1]
	v_mov_b32_e32 v4, v156
	v_mov_b32_e32 v5, v157
	v_mov_b32_e32 v6, v158
	v_mov_b32_e32 v7, v159
	v_mov_b32_e32 v14, v160
	v_mov_b32_e32 v15, v161
	v_mov_b32_e32 v16, v162
	v_mov_b32_e32 v17, v163
	s_cmp_lt_u32 s14, 4
	s_waitcnt vmcnt(0) lgkmcnt(0)
	v_lshlrev_b32_e32 v10, 16, v7
	v_lshlrev_b32_e32 v26, 16, v4
	v_and_b32_e32 v27, 0xffff0000, v4
	v_lshlrev_b32_e32 v24, 16, v14
	v_and_b32_e32 v25, 0xffff0000, v14
	v_lshlrev_b32_e32 v22, 16, v5
	v_and_b32_e32 v23, 0xffff0000, v5
	v_lshlrev_b32_e32 v20, 16, v15
	v_and_b32_e32 v21, 0xffff0000, v15
	v_lshlrev_b32_e32 v18, 16, v6
	v_and_b32_e32 v19, 0xffff0000, v6
	v_lshlrev_b32_e32 v12, 16, v16
	v_and_b32_e32 v13, 0xffff0000, v16
	v_lshlrev_b32_e32 v16, 16, v17
	v_and_b32_e32 v15, 0xffff0000, v7
	v_and_b32_e32 v14, 0xffff0000, v17
	s_cbranch_scc1 .LBB0_177
	v_or_b32_e32 v0, s5, v2
	v_readlane_b32 s8, v254, 28
	v_lshlrev_b32_e32 v0, 8, v0
	v_readlane_b32 s9, v254, 29
	s_nop 1
	v_lshl_add_u64 v[4:5], s[8:9], 0, v[0:1]
	v_lshlrev_b32_e32 v0, 3, v29
	v_lshl_add_u64 v[8:9], v[4:5], 0, v[0:1]
	global_load_dwordx4 v[4:7], v[8:9], off
	global_load_dwordx4 v[30:33], v[8:9], off offset:16
	global_load_dwordx4 v[36:39], v[8:9], off offset:32
	global_load_dwordx4 v[40:43], v[8:9], off offset:48
	s_waitcnt vmcnt(0) lgkmcnt(0)
	v_mov_b32_e32 v8, v4
	v_mov_b32_e32 v9, v6
	v_mov_b32_e32 v6, v5
	v_mov_b32_e32 v4, v30
	v_mov_b32_e32 v5, v32
	v_mov_b32_e32 v32, v31
	v_mov_b32_e32 v30, v36
	v_mov_b32_e32 v31, v38
	v_mov_b32_e32 v38, v37
	v_mul_f32_e32 v36, v40, v10
	v_mul_f32_e32 v46, v41, v10
	v_pk_mul_f32 v[10:11], v[42:43], v[14:15] op_sel:[0,1] op_sel_hi:[1,0]
	v_pk_mul_f32 v[14:15], v[42:43], v[14:15]
	v_mul_f32_e32 v44, v41, v16
	v_mul_f32_e32 v16, v40, v16
	v_pk_mul_f32 v[40:41], v[6:7], v[24:25]
	v_pk_mul_f32 v[42:43], v[32:33], v[20:21]
	v_pk_mul_f32 v[48:49], v[38:39], v[12:13]
	v_mov_b32_e32 v37, v10
	v_mov_b32_e32 v45, v11
	v_mov_b32_e32 v47, v15
	v_mov_b32_e32 v17, v14
	v_pk_mul_f32 v[24:25], v[8:9], v[24:25]
	v_pk_mul_f32 v[20:21], v[4:5], v[20:21]
	v_pk_mul_f32 v[12:13], v[30:31], v[12:13]
	v_pk_fma_f32 v[8:9], v[8:9], v[26:27], v[40:41] neg_lo:[0,0,1] neg_hi:[0,0,1]
	v_pk_fma_f32 v[4:5], v[4:5], v[22:23], v[42:43] neg_lo:[0,0,1] neg_hi:[0,0,1]
	v_pk_fma_f32 v[30:31], v[30:31], v[18:19], v[48:49] neg_lo:[0,0,1] neg_hi:[0,0,1]
	v_pk_add_f32 v[10:11], v[36:37], v[44:45] neg_lo:[0,1] neg_hi:[0,1]
	v_pk_add_f32 v[16:17], v[46:47], v[16:17]
	v_pk_fma_f32 v[24:25], v[6:7], v[26:27], v[24:25]
	v_pk_fma_f32 v[20:21], v[32:33], v[22:23], v[20:21]
	v_pk_fma_f32 v[12:13], v[38:39], v[18:19], v[12:13]
	v_mov_b32_e32 v14, v17
	v_mov_b32_e32 v26, v8
	v_mov_b32_e32 v27, v9
	v_mov_b32_e32 v22, v4
	v_mov_b32_e32 v23, v5
	v_mov_b32_e32 v18, v30
	v_mov_b32_e32 v19, v31
	v_mov_b32_e32 v15, v11
